# v021 + attention-A softmax: cross-half max exchange by v_permlane32_swap instead of ds_bpermute, counted lgkmcnt before first PV MFMA
# speedup vs baseline: 1.0081x; 1.0070x over previous
; #define ATT_VREAD(dst, q_) do { const LAS char* vp_ = (const LAS char*)vb + (((q_) >> 1) * 32 + 16 * ((q_) & 1)) * VSTR; \
;         _Pragma("unroll") for (int d_ = 0; d_ < 4; ++d_) { dst[d_][0] = vtr(vp_ + voff[d_][0]); dst[d_][1] = vtr(vp_ + 8 * VSTR + voff[d_][1]); } } while (0)
;     ...
;         float mx = fmaxf(s0[0], s1[0]);
; #pragma unroll
;         for (int r = 1; r < 16; ++r) mx = fmaxf(mx, fmaxf(s0[r], s1[r]));
;         mx = fmaxf(mx, __shfl_xor(mx, 32));
;         const bool need = mx > mrun + 8.f;
;         if (__any(need)) { const float mnew = need ? mx : mrun, alpha = __builtin_amdgcn_exp2f(mrun - mnew); mrun = mnew; lrun *= alpha;
; #pragma unroll
;             for (int d = 0; d < 4; ++d)
; #pragma unroll
;                 for (int r = 0; r < 16; ++r) o[d][r] *= alpha; }
;     ...
;             if (wka) { vb = sa + KBUF + vlane; ATT_VREAD(vpre, 0); SM(wa0, wa1, a0, a1, pba);
.LBB0_586:
	v_add_u32_e32 v148, s1, v194
	s_andn2_b64 vcc, exec, s[28:29]
	v_add_u32_e32 v200, v148, v186
	v_add_u32_e32 v201, v148, v187
	v_add_u32_e32 v202, v148, v188
	v_add_u32_e32 v203, v148, v189
	v_add_u32_e32 v204, v148, v190
	v_add_u32_e32 v205, v148, v191
	v_add_u32_e32 v206, v148, v192
	v_add_u32_e32 v207, v148, v193
	s_cbranch_vccnz .LBB0_590
	v_max_f32_e32 v156, v101, v101
	v_max_f32_e32 v157, v69, v69
	v_max_f32_e32 v156, v157, v156
	v_max_f32_e32 v157, v102, v102
	v_max_f32_e32 v158, v70, v70
	v_max_f32_e32 v157, v158, v157
	v_max_f32_e32 v158, v103, v103
	v_max_f32_e32 v159, v71, v71
	v_max3_f32 v156, v68, v100, v156
	v_max_f32_e32 v158, v159, v158
	v_max3_f32 v156, v156, v157, v158
	v_max_f32_e32 v157, v104, v104
	v_max_f32_e32 v158, v72, v72
	v_max_f32_e32 v157, v158, v157
	v_max_f32_e32 v158, v105, v105
	v_max_f32_e32 v159, v73, v73
	v_max_f32_e32 v158, v159, v158
	v_max3_f32 v156, v156, v157, v158
	v_max_f32_e32 v157, v106, v106
	v_max_f32_e32 v158, v74, v74
	v_max_f32_e32 v157, v158, v157
	v_max_f32_e32 v158, v107, v107
	v_max_f32_e32 v159, v75, v75
	v_max_f32_e32 v158, v159, v158
	v_max3_f32 v156, v156, v157, v158
	v_max_f32_e32 v157, v108, v108
	v_max_f32_e32 v158, v76, v76
	v_max_f32_e32 v157, v158, v157
	v_max_f32_e32 v158, v109, v109
	v_max_f32_e32 v159, v77, v77
	v_max_f32_e32 v158, v159, v158
	v_max3_f32 v156, v156, v157, v158
	v_max_f32_e32 v157, v110, v110
	v_max_f32_e32 v158, v78, v78
	v_max_f32_e32 v157, v158, v157
	v_max_f32_e32 v158, v111, v111
	v_max_f32_e32 v159, v79, v79
	v_max_f32_e32 v158, v159, v158
	v_max3_f32 v156, v156, v157, v158
	v_max_f32_e32 v157, v112, v112
	v_max_f32_e32 v158, v80, v80
	v_max_f32_e32 v157, v158, v157
	v_max_f32_e32 v158, v113, v113
	v_max_f32_e32 v159, v81, v81
	v_max_f32_e32 v158, v159, v158
	v_max3_f32 v156, v156, v157, v158
	v_max_f32_e32 v157, v114, v114
	v_max_f32_e32 v158, v82, v82
	v_max_f32_e32 v157, v158, v157
	v_max_f32_e32 v158, v115, v115
	v_max_f32_e32 v159, v83, v83
	v_max_f32_e32 v158, v159, v158
	v_max3_f32 v208, v156, v157, v158
	s_waitcnt vmcnt(0)
	ds_read_b64_tr_b16 v[152:153], v200 offset:16384
	ds_read_b64_tr_b16 v[154:155], v201 offset:18432
	ds_read_b64_tr_b16 v[148:149], v202 offset:16384
	ds_read_b64_tr_b16 v[150:151], v203 offset:18432
	v_mov_b32_e32 v246, v208
	v_mov_b32_e32 v247, v208
	ds_read_b64_tr_b16 v[160:161], v204 offset:16384
	ds_read_b64_tr_b16 v[162:163], v205 offset:18432
	ds_read_b64_tr_b16 v[156:157], v206 offset:16384
	ds_read_b64_tr_b16 v[158:159], v207 offset:18432
	v_permlane32_swap_b32_e32 v246, v247
	v_max3_f32 v208, v208, v246, v247
	v_add_f32_e32 v209, 0x41000000, v170
	v_cmp_gt_f32_e32 vcc, v208, v209
	s_cbranch_vccz .LBB0_589
	s_nop 0
	v_cndmask_b32_e32 v208, v170, v208, vcc
	v_sub_f32_e32 v170, v170, v208
	v_exp_f32_e32 v170, v170
	s_nop 0
	v_mul_f32_e32 v167, v167, v170
	v_pk_mul_f32 v[66:67], v[66:67], v[170:171] op_sel_hi:[1,0]
	v_pk_mul_f32 v[64:65], v[64:65], v[170:171] op_sel_hi:[1,0]
	v_pk_mul_f32 v[62:63], v[62:63], v[170:171] op_sel_hi:[1,0]
	v_pk_mul_f32 v[60:61], v[60:61], v[170:171] op_sel_hi:[1,0]
	v_pk_mul_f32 v[58:59], v[58:59], v[170:171] op_sel_hi:[1,0]
	v_pk_mul_f32 v[56:57], v[56:57], v[170:171] op_sel_hi:[1,0]
	v_pk_mul_f32 v[54:55], v[54:55], v[170:171] op_sel_hi:[1,0]
	v_pk_mul_f32 v[52:53], v[52:53], v[170:171] op_sel_hi:[1,0]
	v_pk_mul_f32 v[50:51], v[50:51], v[170:171] op_sel_hi:[1,0]
	v_pk_mul_f32 v[48:49], v[48:49], v[170:171] op_sel_hi:[1,0]
	v_pk_mul_f32 v[46:47], v[46:47], v[170:171] op_sel_hi:[1,0]
	v_pk_mul_f32 v[44:45], v[44:45], v[170:171] op_sel_hi:[1,0]
	v_pk_mul_f32 v[42:43], v[42:43], v[170:171] op_sel_hi:[1,0]
	v_pk_mul_f32 v[40:41], v[40:41], v[170:171] op_sel_hi:[1,0]
	v_pk_mul_f32 v[38:39], v[38:39], v[170:171] op_sel_hi:[1,0]
	v_pk_mul_f32 v[36:37], v[36:37], v[170:171] op_sel_hi:[1,0]
	v_pk_mul_f32 v[34:35], v[34:35], v[170:171] op_sel_hi:[1,0]
	v_pk_mul_f32 v[32:33], v[32:33], v[170:171] op_sel_hi:[1,0]
	v_pk_mul_f32 v[30:31], v[30:31], v[170:171] op_sel_hi:[1,0]
	v_pk_mul_f32 v[28:29], v[28:29], v[170:171] op_sel_hi:[1,0]
	v_pk_mul_f32 v[26:27], v[26:27], v[170:171] op_sel_hi:[1,0]
	v_pk_mul_f32 v[24:25], v[24:25], v[170:171] op_sel_hi:[1,0]
	v_pk_mul_f32 v[22:23], v[22:23], v[170:171] op_sel_hi:[1,0]
	v_pk_mul_f32 v[20:21], v[20:21], v[170:171] op_sel_hi:[1,0]
	v_pk_mul_f32 v[18:19], v[18:19], v[170:171] op_sel_hi:[1,0]
	v_pk_mul_f32 v[16:17], v[16:17], v[170:171] op_sel_hi:[1,0]
	v_pk_mul_f32 v[14:15], v[14:15], v[170:171] op_sel_hi:[1,0]
	v_pk_mul_f32 v[12:13], v[12:13], v[170:171] op_sel_hi:[1,0]
	v_pk_mul_f32 v[10:11], v[10:11], v[170:171] op_sel_hi:[1,0]
	v_pk_mul_f32 v[8:9], v[8:9], v[170:171] op_sel_hi:[1,0]
	v_pk_mul_f32 v[6:7], v[6:7], v[170:171] op_sel_hi:[1,0]
	v_pk_mul_f32 v[4:5], v[4:5], v[170:171] op_sel_hi:[1,0]
	v_mov_b32_e32 v170, v208
; __device__ __forceinline__ unsigned cvtpk(float lo, float hi) { typedef __bf16 b2 __attribute__((ext_vector_type(2))); f32x2 v = {lo, hi}; b2 b = __builtin_convertvector(v, b2); return __builtin_bit_cast(unsigned, b); }
; __device__ __forceinline__ int crow(int r, int hi) { return (r & 3) + 8 * (r >> 2) + 4 * hi; }
; #define ATT_VREAD(dst, q_) do { const LAS char* vp_ = (const LAS char*)vb + (((q_) >> 1) * 32 + 16 * ((q_) & 1)) * VSTR; \
;         _Pragma("unroll") for (int d_ = 0; d_ < 4; ++d_) { dst[d_][0] = vtr(vp_ + voff[d_][0]); dst[d_][1] = vtr(vp_ + 8 * VSTR + voff[d_][1]); } } while (0)
;     ...
;         float rsa[4] = {0.f, 0.f, 0.f, 0.f};
; #pragma unroll
;         for (int r = 0; r < 16; ++r) { float p0 = __builtin_amdgcn_exp2f(s0[r] - mrun), p1 = __builtin_amdgcn_exp2f(s1[r] - mrun);
;             if (LAYER == 1) { const int kv = crow(r, hi); p0 = ((w0 >> kv) & 1u) ? p0 : 0.f; p1 = ((w1 >> kv) & 1u) ? p1 : 0.f; }
;             s0[r] = p0; s1[r] = p1; rsa[r & 3] += p0 + p1; }
;         lrun += (rsa[0] + rsa[1]) + (rsa[2] + rsa[3]);
; #pragma unroll
;         for (int s = 0; s < 2; ++s) {
;             v4u x; x.x = cvtpk(s0[8 * s + 0], s0[8 * s + 1]); x.y = cvtpk(s0[8 * s + 2], s0[8 * s + 3]); x.z = cvtpk(s0[8 * s + 4], s0[8 * s + 5]); x.w = cvtpk(s0[8 * s + 6], s0[8 * s + 7]); pb[0][s] = __builtin_bit_cast(bf16x8, x);
;             v4u y; y.x = cvtpk(s1[8 * s + 0], s1[8 * s + 1]); y.y = cvtpk(s1[8 * s + 2], s1[8 * s + 3]); y.z = cvtpk(s1[8 * s + 4], s1[8 * s + 5]); y.w = cvtpk(s1[8 * s + 6], s1[8 * s + 7]); pb[1][s] = __builtin_bit_cast(bf16x8, y); }
;     ...
;             if (wka) { vb = sa + KBUF + vlane; ATT_VREAD(vpre, 0); SM(wa0, wa1, a0, a1, pba);
;                 ATT_VREAD(va, 1); __builtin_amdgcn_s_setprio(1); ATT_PV(vpre, pba, 0); __builtin_amdgcn_s_setprio(0);
;                 ATT_VREAD(vbb, 2); __builtin_amdgcn_s_setprio(1); ATT_PV(va, pba, 1); __builtin_amdgcn_s_setprio(0);
;                 ATT_VREAD(va, 3); __builtin_amdgcn_s_setprio(1); ATT_PV(vbb, pba, 2); __builtin_amdgcn_s_setprio(0);
;                 __builtin_amdgcn_s_setprio(1); ATT_PV(va, pba, 3); __builtin_amdgcn_s_setprio(0); }
.LBB0_589:
	v_sub_f32_e32 v68, v68, v170
	v_sub_f32_e32 v100, v100, v170
	v_sub_f32_e32 v70, v70, v170
	v_sub_f32_e32 v102, v102, v170
	v_exp_f32_e32 v68, v68
	v_exp_f32_e32 v100, v100
	v_sub_f32_e32 v69, v69, v170
	v_sub_f32_e32 v101, v101, v170
	v_exp_f32_e32 v70, v70
	v_exp_f32_e32 v102, v102
	v_sub_f32_e32 v71, v71, v170
	v_sub_f32_e32 v103, v103, v170
	v_exp_f32_e32 v69, v69
	v_exp_f32_e32 v101, v101
	v_exp_f32_e32 v71, v71
	v_exp_f32_e32 v103, v103
	v_sub_f32_e32 v72, v72, v170
	v_sub_f32_e32 v104, v104, v170
	v_sub_f32_e32 v74, v74, v170
	v_sub_f32_e32 v106, v106, v170
	v_exp_f32_e32 v72, v72
	v_exp_f32_e32 v104, v104
	v_exp_f32_e32 v74, v74
	v_exp_f32_e32 v106, v106
	v_sub_f32_e32 v73, v73, v170
	v_sub_f32_e32 v105, v105, v170
	v_sub_f32_e32 v75, v75, v170
	v_sub_f32_e32 v107, v107, v170
	v_exp_f32_e32 v73, v73
	v_exp_f32_e32 v105, v105
	v_exp_f32_e32 v75, v75
	v_exp_f32_e32 v107, v107
	v_mov_b32_e32 v208, v68
	v_mov_b32_e32 v209, v70
	v_mov_b32_e32 v210, v100
	v_mov_b32_e32 v211, v102
	v_sub_f32_e32 v76, v76, v170
	v_sub_f32_e32 v108, v108, v170
	v_sub_f32_e32 v78, v78, v170
	v_sub_f32_e32 v110, v110, v170
	v_pk_add_f32 v[208:209], v[208:209], v[210:211]
	v_mov_b32_e32 v210, v69
	v_mov_b32_e32 v211, v71
	v_mov_b32_e32 v212, v101
	v_mov_b32_e32 v213, v103
	v_exp_f32_e32 v76, v76
	v_exp_f32_e32 v108, v108
	v_exp_f32_e32 v78, v78
	v_exp_f32_e32 v110, v110
	v_pk_add_f32 v[210:211], v[210:211], v[212:213]
	v_mov_b32_e32 v212, v72
	v_mov_b32_e32 v213, v74
	v_mov_b32_e32 v214, v104
	v_mov_b32_e32 v215, v106
	v_sub_f32_e32 v77, v77, v170
	v_sub_f32_e32 v109, v109, v170
	v_sub_f32_e32 v79, v79, v170
	v_sub_f32_e32 v111, v111, v170
	v_pk_add_f32 v[208:209], v[208:209], 0 op_sel_hi:[1,0]
	v_pk_add_f32 v[212:213], v[212:213], v[214:215]
	v_exp_f32_e32 v77, v77
	v_exp_f32_e32 v109, v109
	v_exp_f32_e32 v79, v79
	v_exp_f32_e32 v111, v111
	v_pk_add_f32 v[208:209], v[212:213], v[208:209]
	v_mov_b32_e32 v212, v73
	v_mov_b32_e32 v213, v75
	v_mov_b32_e32 v214, v105
	v_mov_b32_e32 v215, v107
	v_sub_f32_e32 v80, v80, v170
	v_sub_f32_e32 v112, v112, v170
	v_sub_f32_e32 v82, v82, v170
	v_sub_f32_e32 v114, v114, v170
	v_pk_add_f32 v[210:211], v[210:211], 0 op_sel_hi:[1,0]
	v_pk_add_f32 v[212:213], v[212:213], v[214:215]
	ds_read_b64_tr_b16 v[220:221], v200 offset:20480
	ds_read_b64_tr_b16 v[222:223], v201 offset:22528
	ds_read_b64_tr_b16 v[224:225], v202 offset:20480
	ds_read_b64_tr_b16 v[226:227], v203 offset:22528
	ds_read_b64_tr_b16 v[228:229], v204 offset:20480
	ds_read_b64_tr_b16 v[230:231], v205 offset:22528
	ds_read_b64_tr_b16 v[232:233], v206 offset:20480
	ds_read_b64_tr_b16 v[234:235], v207 offset:22528
	v_exp_f32_e32 v80, v80
	v_exp_f32_e32 v112, v112
	v_exp_f32_e32 v82, v82
	v_exp_f32_e32 v114, v114
	v_pk_add_f32 v[210:211], v[212:213], v[210:211]
	v_mov_b32_e32 v212, v76
	v_mov_b32_e32 v213, v78
	v_mov_b32_e32 v214, v108
	v_mov_b32_e32 v215, v110
	v_sub_f32_e32 v81, v81, v170
	v_sub_f32_e32 v113, v113, v170
	v_sub_f32_e32 v83, v83, v170
	v_sub_f32_e32 v115, v115, v170
	v_pk_add_f32 v[212:213], v[212:213], v[214:215]
	v_exp_f32_e32 v81, v81
	v_exp_f32_e32 v113, v113
	v_exp_f32_e32 v83, v83
	v_exp_f32_e32 v115, v115
	v_pk_add_f32 v[208:209], v[212:213], v[208:209]
	v_mov_b32_e32 v212, v77
	v_mov_b32_e32 v213, v79
	v_mov_b32_e32 v214, v109
	v_mov_b32_e32 v215, v111
	v_pk_add_f32 v[212:213], v[212:213], v[214:215]
	v_mov_b32_e32 v214, v112
	v_pk_add_f32 v[210:211], v[212:213], v[210:211]
	v_mov_b32_e32 v212, v80
	v_mov_b32_e32 v213, v82
	v_mov_b32_e32 v215, v114
	v_pk_add_f32 v[212:213], v[212:213], v[214:215]
	v_mov_b32_e32 v214, v113
	v_pk_add_f32 v[208:209], v[212:213], v[208:209]
	v_mov_b32_e32 v212, v81
	v_mov_b32_e32 v213, v83
	v_mov_b32_e32 v215, v115
	v_pk_add_f32 v[212:213], v[212:213], v[214:215]
	v_cvt_pk_bf16_f32 v214, v104, v105
	v_pk_add_f32 v[210:211], v[212:213], v[210:211]
	v_cvt_pk_bf16_f32 v212, v100, v101
	v_pk_add_f32 v[208:209], v[208:209], v[210:211]
	v_cvt_pk_bf16_f32 v210, v72, v73
	v_add_f32_e32 v240, v208, v209
	v_cvt_pk_bf16_f32 v208, v68, v69
	v_cvt_pk_bf16_f32 v209, v70, v71
	v_cvt_pk_bf16_f32 v211, v74, v75
	v_cvt_pk_bf16_f32 v213, v102, v103
	v_cvt_pk_bf16_f32 v215, v106, v107
	v_cvt_pk_bf16_f32 v216, v76, v77
	v_cvt_pk_bf16_f32 v217, v78, v79
	v_cvt_pk_bf16_f32 v218, v80, v81
	v_cvt_pk_bf16_f32 v219, v82, v83
	v_cvt_pk_bf16_f32 v236, v108, v109
	v_cvt_pk_bf16_f32 v237, v110, v111
	v_cvt_pk_bf16_f32 v238, v112, v113
	v_cvt_pk_bf16_f32 v239, v114, v115
	s_setprio 1
	s_waitcnt lgkmcnt(8)
	v_mfma_f32_32x32x16_bf16 v[52:67], v[152:155], v[208:211], v[52:67]
	v_add_f32_e32 v167, v167, v240
	v_mfma_f32_32x32x16_bf16 v[36:51], v[148:151], v[208:211], v[36:51]
	v_mfma_f32_32x32x16_bf16 v[20:35], v[160:163], v[208:211], v[20:35]
	v_mfma_f32_32x32x16_bf16 v[4:19], v[156:159], v[208:211], v[4:19]
	s_setprio 0
	ds_read_b64_tr_b16 v[148:149], v200 offset:24576
	ds_read_b64_tr_b16 v[150:151], v201 offset:26624
	ds_read_b64_tr_b16 v[152:153], v202 offset:24576
	ds_read_b64_tr_b16 v[154:155], v203 offset:26624
	ds_read_b64_tr_b16 v[156:157], v204 offset:24576
	ds_read_b64_tr_b16 v[158:159], v205 offset:26624
	ds_read_b64_tr_b16 v[160:161], v206 offset:24576
	ds_read_b64_tr_b16 v[162:163], v207 offset:26624
	s_setprio 1
	s_waitcnt lgkmcnt(14)
	v_mfma_f32_32x32x16_bf16 v[52:67], v[220:223], v[216:219], v[52:67]
	s_waitcnt lgkmcnt(12)
	v_mfma_f32_32x32x16_bf16 v[36:51], v[224:227], v[216:219], v[36:51]
	s_waitcnt lgkmcnt(10)
	v_mfma_f32_32x32x16_bf16 v[20:35], v[228:231], v[216:219], v[20:35]
	s_waitcnt lgkmcnt(8)
	v_mfma_f32_32x32x16_bf16 v[4:19], v[232:235], v[216:219], v[4:19]
	s_setprio 0
	ds_read_b64_tr_b16 v[208:209], v200 offset:28672
	ds_read_b64_tr_b16 v[210:211], v201 offset:30720
	ds_read_b64_tr_b16 v[216:217], v202 offset:28672
	ds_read_b64_tr_b16 v[218:219], v203 offset:30720
	ds_read_b64_tr_b16 v[220:221], v204 offset:28672
	ds_read_b64_tr_b16 v[222:223], v205 offset:30720
	ds_read_b64_tr_b16 v[224:225], v206 offset:28672
	ds_read_b64_tr_b16 v[226:227], v207 offset:30720
	s_setprio 1
	s_waitcnt lgkmcnt(14)
	v_mfma_f32_32x32x16_bf16 v[52:67], v[148:151], v[212:215], v[52:67]
	s_waitcnt lgkmcnt(12)
	v_mfma_f32_32x32x16_bf16 v[36:51], v[152:155], v[212:215], v[36:51]
	s_waitcnt lgkmcnt(10)
	v_mfma_f32_32x32x16_bf16 v[20:35], v[156:159], v[212:215], v[20:35]
	s_waitcnt lgkmcnt(8)
	v_mfma_f32_32x32x16_bf16 v[4:19], v[160:163], v[212:215], v[4:19]
	s_setprio 0
	s_setprio 1
	s_waitcnt lgkmcnt(6)
	v_mfma_f32_32x32x16_bf16 v[52:67], v[208:211], v[236:239], v[52:67]
	s_waitcnt lgkmcnt(4)
	v_mfma_f32_32x32x16_bf16 v[36:51], v[216:219], v[236:239], v[36:51]
	s_waitcnt lgkmcnt(2)
	v_mfma_f32_32x32x16_bf16 v[20:35], v[220:223], v[236:239], v[20:35]
	s_waitcnt lgkmcnt(0)
	v_mfma_f32_32x32x16_bf16 v[4:19], v[224:227], v[236:239], v[4:19]
	s_setprio 0
; #define ATT_VREAD(dst, q_) do { const LAS char* vp_ = (const LAS char*)vb + (((q_) >> 1) * 32 + 16 * ((q_) & 1)) * VSTR; \
;         _Pragma("unroll") for (int d_ = 0; d_ < 4; ++d_) { dst[d_][0] = vtr(vp_ + voff[d_][0]); dst[d_][1] = vtr(vp_ + 8 * VSTR + voff[d_][1]); } } while (0)
;     ...
;         float mx = fmaxf(s0[0], s1[0]);
; #pragma unroll
;         for (int r = 1; r < 16; ++r) mx = fmaxf(mx, fmaxf(s0[r], s1[r]));
;         mx = fmaxf(mx, __shfl_xor(mx, 32));
;         const bool need = mx > mrun + 8.f;
;         if (__any(need)) { const float mnew = need ? mx : mrun, alpha = __builtin_amdgcn_exp2f(mrun - mnew); mrun = mnew; lrun *= alpha;
; #pragma unroll
;             for (int d = 0; d < 4; ++d)
; #pragma unroll
;                 for (int r = 0; r < 16; ++r) o[d][r] *= alpha; }
;     ...
;             if (wkb) { vb = sbb + KBUF + vlane; ATT_VREAD(vpre, 0); SM(wb0, wb1, b0, b1, pbb);
.LBB0_590:
	s_and_b64 vcc, exec, s[2:3]
	s_cbranch_vccnz .LBB0_594
	v_max_f32_e32 v156, v117, v117
	v_max_f32_e32 v157, v85, v85
	v_max_f32_e32 v156, v157, v156
	v_max_f32_e32 v157, v118, v118
	v_max_f32_e32 v158, v86, v86
	v_max_f32_e32 v157, v158, v157
	v_max_f32_e32 v158, v119, v119
	v_max_f32_e32 v159, v87, v87
	v_max3_f32 v156, v84, v116, v156
	v_max_f32_e32 v158, v159, v158
	v_max3_f32 v156, v156, v157, v158
	v_max_f32_e32 v157, v120, v120
	v_max_f32_e32 v158, v88, v88
	v_max_f32_e32 v157, v158, v157
	v_max_f32_e32 v158, v121, v121
	v_max_f32_e32 v159, v89, v89
	v_max_f32_e32 v158, v159, v158
	v_max3_f32 v156, v156, v157, v158
	v_max_f32_e32 v157, v122, v122
	v_max_f32_e32 v158, v90, v90
	v_max_f32_e32 v157, v158, v157
	v_max_f32_e32 v158, v123, v123
	v_max_f32_e32 v159, v91, v91
	v_max_f32_e32 v158, v159, v158
	v_max3_f32 v156, v156, v157, v158
	v_max_f32_e32 v157, v124, v124
	v_max_f32_e32 v158, v92, v92
	v_max_f32_e32 v157, v158, v157
	v_max_f32_e32 v158, v125, v125
	v_max_f32_e32 v159, v93, v93
	v_max_f32_e32 v158, v159, v158
	v_max3_f32 v156, v156, v157, v158
	v_max_f32_e32 v157, v126, v126
	v_max_f32_e32 v158, v94, v94
	v_max_f32_e32 v157, v158, v157
	v_max_f32_e32 v158, v127, v127
	v_max_f32_e32 v159, v95, v95
	v_max_f32_e32 v158, v159, v158
	v_max3_f32 v156, v156, v157, v158
	v_max_f32_e32 v157, v128, v128
	v_max_f32_e32 v158, v96, v96
	v_max_f32_e32 v157, v158, v157
	v_max_f32_e32 v158, v129, v129
	v_max_f32_e32 v159, v97, v97
	v_max_f32_e32 v158, v159, v158
	v_max3_f32 v156, v156, v157, v158
	v_max_f32_e32 v157, v130, v130
	v_max_f32_e32 v158, v98, v98
	v_max_f32_e32 v157, v158, v157
	v_max_f32_e32 v158, v131, v131
	v_max_f32_e32 v159, v99, v99
	v_max_f32_e32 v158, v159, v158
	v_max3_f32 v208, v156, v157, v158
	s_waitcnt vmcnt(0)
	ds_read_b64_tr_b16 v[152:153], v200 offset:49152
	ds_read_b64_tr_b16 v[154:155], v201 offset:51200
	ds_read_b64_tr_b16 v[148:149], v202 offset:49152
	ds_read_b64_tr_b16 v[150:151], v203 offset:51200
	v_mov_b32_e32 v246, v208
	v_mov_b32_e32 v247, v208
	ds_read_b64_tr_b16 v[160:161], v204 offset:49152
	ds_read_b64_tr_b16 v[162:163], v205 offset:51200
	ds_read_b64_tr_b16 v[156:157], v206 offset:49152
	ds_read_b64_tr_b16 v[158:159], v207 offset:51200
	v_permlane32_swap_b32_e32 v246, v247
	v_max3_f32 v208, v208, v246, v247
	v_add_f32_e32 v209, 0x41000000, v170
	v_cmp_gt_f32_e32 vcc, v208, v209
	s_cbranch_vccz .LBB0_593
	s_nop 0
	v_cndmask_b32_e32 v208, v170, v208, vcc
	v_sub_f32_e32 v170, v170, v208
	v_exp_f32_e32 v170, v170
	s_nop 0
	v_mul_f32_e32 v167, v167, v170
	v_pk_mul_f32 v[66:67], v[66:67], v[170:171] op_sel_hi:[1,0]
	v_pk_mul_f32 v[64:65], v[64:65], v[170:171] op_sel_hi:[1,0]
	v_pk_mul_f32 v[62:63], v[62:63], v[170:171] op_sel_hi:[1,0]
	v_pk_mul_f32 v[60:61], v[60:61], v[170:171] op_sel_hi:[1,0]
	v_pk_mul_f32 v[58:59], v[58:59], v[170:171] op_sel_hi:[1,0]
	v_pk_mul_f32 v[56:57], v[56:57], v[170:171] op_sel_hi:[1,0]
	v_pk_mul_f32 v[54:55], v[54:55], v[170:171] op_sel_hi:[1,0]
	v_pk_mul_f32 v[52:53], v[52:53], v[170:171] op_sel_hi:[1,0]
	v_pk_mul_f32 v[50:51], v[50:51], v[170:171] op_sel_hi:[1,0]
	v_pk_mul_f32 v[48:49], v[48:49], v[170:171] op_sel_hi:[1,0]
	v_pk_mul_f32 v[46:47], v[46:47], v[170:171] op_sel_hi:[1,0]
	v_pk_mul_f32 v[44:45], v[44:45], v[170:171] op_sel_hi:[1,0]
	v_pk_mul_f32 v[42:43], v[42:43], v[170:171] op_sel_hi:[1,0]
	v_pk_mul_f32 v[40:41], v[40:41], v[170:171] op_sel_hi:[1,0]
	v_pk_mul_f32 v[38:39], v[38:39], v[170:171] op_sel_hi:[1,0]
	v_pk_mul_f32 v[36:37], v[36:37], v[170:171] op_sel_hi:[1,0]
	v_pk_mul_f32 v[34:35], v[34:35], v[170:171] op_sel_hi:[1,0]
	v_pk_mul_f32 v[32:33], v[32:33], v[170:171] op_sel_hi:[1,0]
	v_pk_mul_f32 v[30:31], v[30:31], v[170:171] op_sel_hi:[1,0]
	v_pk_mul_f32 v[28:29], v[28:29], v[170:171] op_sel_hi:[1,0]
	v_pk_mul_f32 v[26:27], v[26:27], v[170:171] op_sel_hi:[1,0]
	v_pk_mul_f32 v[24:25], v[24:25], v[170:171] op_sel_hi:[1,0]
	v_pk_mul_f32 v[22:23], v[22:23], v[170:171] op_sel_hi:[1,0]
	v_pk_mul_f32 v[20:21], v[20:21], v[170:171] op_sel_hi:[1,0]
	v_pk_mul_f32 v[18:19], v[18:19], v[170:171] op_sel_hi:[1,0]
	v_pk_mul_f32 v[16:17], v[16:17], v[170:171] op_sel_hi:[1,0]
	v_pk_mul_f32 v[14:15], v[14:15], v[170:171] op_sel_hi:[1,0]
	v_pk_mul_f32 v[12:13], v[12:13], v[170:171] op_sel_hi:[1,0]
	v_pk_mul_f32 v[10:11], v[10:11], v[170:171] op_sel_hi:[1,0]
	v_pk_mul_f32 v[8:9], v[8:9], v[170:171] op_sel_hi:[1,0]
	v_pk_mul_f32 v[6:7], v[6:7], v[170:171] op_sel_hi:[1,0]
	v_pk_mul_f32 v[4:5], v[4:5], v[170:171] op_sel_hi:[1,0]
	v_mov_b32_e32 v170, v208
; __device__ __forceinline__ unsigned cvtpk(float lo, float hi) { typedef __bf16 b2 __attribute__((ext_vector_type(2))); f32x2 v = {lo, hi}; b2 b = __builtin_convertvector(v, b2); return __builtin_bit_cast(unsigned, b); }
; __device__ __forceinline__ int crow(int r, int hi) { return (r & 3) + 8 * (r >> 2) + 4 * hi; }
; #define ATT_VREAD(dst, q_) do { const LAS char* vp_ = (const LAS char*)vb + (((q_) >> 1) * 32 + 16 * ((q_) & 1)) * VSTR; \
;         _Pragma("unroll") for (int d_ = 0; d_ < 4; ++d_) { dst[d_][0] = vtr(vp_ + voff[d_][0]); dst[d_][1] = vtr(vp_ + 8 * VSTR + voff[d_][1]); } } while (0)
;     ...
;         float rsa[4] = {0.f, 0.f, 0.f, 0.f};
; #pragma unroll
;         for (int r = 0; r < 16; ++r) { float p0 = __builtin_amdgcn_exp2f(s0[r] - mrun), p1 = __builtin_amdgcn_exp2f(s1[r] - mrun);
;             if (LAYER == 1) { const int kv = crow(r, hi); p0 = ((w0 >> kv) & 1u) ? p0 : 0.f; p1 = ((w1 >> kv) & 1u) ? p1 : 0.f; }
;             s0[r] = p0; s1[r] = p1; rsa[r & 3] += p0 + p1; }
;         lrun += (rsa[0] + rsa[1]) + (rsa[2] + rsa[3]);
; #pragma unroll
;         for (int s = 0; s < 2; ++s) {
;             v4u x; x.x = cvtpk(s0[8 * s + 0], s0[8 * s + 1]); x.y = cvtpk(s0[8 * s + 2], s0[8 * s + 3]); x.z = cvtpk(s0[8 * s + 4], s0[8 * s + 5]); x.w = cvtpk(s0[8 * s + 6], s0[8 * s + 7]); pb[0][s] = __builtin_bit_cast(bf16x8, x);
;             v4u y; y.x = cvtpk(s1[8 * s + 0], s1[8 * s + 1]); y.y = cvtpk(s1[8 * s + 2], s1[8 * s + 3]); y.z = cvtpk(s1[8 * s + 4], s1[8 * s + 5]); y.w = cvtpk(s1[8 * s + 6], s1[8 * s + 7]); pb[1][s] = __builtin_bit_cast(bf16x8, y); }
;     ...
;             if (wkb) { vb = sbb + KBUF + vlane; ATT_VREAD(vpre, 0); SM(wb0, wb1, b0, b1, pbb);
;                 ATT_VREAD(va, 1); __builtin_amdgcn_s_setprio(1); ATT_PV(vpre, pbb, 0); __builtin_amdgcn_s_setprio(0);
;                 ATT_VREAD(vbb, 2); __builtin_amdgcn_s_setprio(1); ATT_PV(va, pbb, 1); __builtin_amdgcn_s_setprio(0);
;                 ATT_VREAD(va, 3); __builtin_amdgcn_s_setprio(1); ATT_PV(vbb, pbb, 2); __builtin_amdgcn_s_setprio(0);
;                 __builtin_amdgcn_s_setprio(1); ATT_PV(va, pbb, 3); __builtin_amdgcn_s_setprio(0); }
.LBB0_593:
	v_sub_f32_e32 v84, v84, v170
	v_sub_f32_e32 v116, v116, v170
	v_sub_f32_e32 v86, v86, v170
	v_sub_f32_e32 v118, v118, v170
	v_exp_f32_e32 v84, v84
	v_exp_f32_e32 v116, v116
	v_sub_f32_e32 v85, v85, v170
	v_sub_f32_e32 v117, v117, v170
	v_exp_f32_e32 v86, v86
	v_exp_f32_e32 v118, v118
	v_sub_f32_e32 v87, v87, v170
	v_sub_f32_e32 v119, v119, v170
	v_exp_f32_e32 v85, v85
	v_exp_f32_e32 v117, v117
	v_exp_f32_e32 v87, v87
	v_exp_f32_e32 v119, v119
	v_sub_f32_e32 v88, v88, v170
	v_sub_f32_e32 v120, v120, v170
	v_sub_f32_e32 v90, v90, v170
	v_sub_f32_e32 v122, v122, v170
	v_exp_f32_e32 v88, v88
	v_exp_f32_e32 v120, v120
	v_exp_f32_e32 v90, v90
	v_exp_f32_e32 v122, v122
	v_sub_f32_e32 v89, v89, v170
	v_sub_f32_e32 v121, v121, v170
	v_sub_f32_e32 v91, v91, v170
	v_sub_f32_e32 v123, v123, v170
	v_exp_f32_e32 v89, v89
	v_exp_f32_e32 v121, v121
	v_exp_f32_e32 v91, v91
	v_exp_f32_e32 v123, v123
	v_mov_b32_e32 v208, v84
	v_mov_b32_e32 v209, v86
	v_mov_b32_e32 v210, v116
	v_mov_b32_e32 v211, v118
	v_sub_f32_e32 v92, v92, v170
	v_sub_f32_e32 v124, v124, v170
	v_sub_f32_e32 v94, v94, v170
	v_sub_f32_e32 v126, v126, v170
	v_pk_add_f32 v[208:209], v[208:209], v[210:211]
	v_mov_b32_e32 v210, v85
	v_mov_b32_e32 v211, v87
	v_mov_b32_e32 v212, v117
	v_mov_b32_e32 v213, v119
	v_exp_f32_e32 v92, v92
	v_exp_f32_e32 v124, v124
	v_exp_f32_e32 v94, v94
	v_exp_f32_e32 v126, v126
	v_pk_add_f32 v[210:211], v[210:211], v[212:213]
	v_mov_b32_e32 v212, v88
	v_mov_b32_e32 v213, v90
	v_mov_b32_e32 v214, v120
	v_mov_b32_e32 v215, v122
	v_sub_f32_e32 v93, v93, v170
	v_sub_f32_e32 v125, v125, v170
	v_sub_f32_e32 v95, v95, v170
	v_sub_f32_e32 v127, v127, v170
	v_pk_add_f32 v[208:209], v[208:209], 0 op_sel_hi:[1,0]
	v_pk_add_f32 v[212:213], v[212:213], v[214:215]
	v_exp_f32_e32 v93, v93
	v_exp_f32_e32 v125, v125
	v_exp_f32_e32 v95, v95
	v_exp_f32_e32 v127, v127
	v_pk_add_f32 v[208:209], v[212:213], v[208:209]
	v_mov_b32_e32 v212, v89
	v_mov_b32_e32 v213, v91
	v_mov_b32_e32 v214, v121
	v_mov_b32_e32 v215, v123
	v_sub_f32_e32 v96, v96, v170
	v_sub_f32_e32 v128, v128, v170
	v_sub_f32_e32 v98, v98, v170
	v_sub_f32_e32 v130, v130, v170
	v_pk_add_f32 v[210:211], v[210:211], 0 op_sel_hi:[1,0]
	v_pk_add_f32 v[212:213], v[212:213], v[214:215]
	ds_read_b64_tr_b16 v[220:221], v200 offset:53248
	ds_read_b64_tr_b16 v[222:223], v201 offset:55296
	ds_read_b64_tr_b16 v[224:225], v202 offset:53248
	ds_read_b64_tr_b16 v[226:227], v203 offset:55296
	ds_read_b64_tr_b16 v[228:229], v204 offset:53248
	ds_read_b64_tr_b16 v[230:231], v205 offset:55296
	ds_read_b64_tr_b16 v[232:233], v206 offset:53248
	ds_read_b64_tr_b16 v[234:235], v207 offset:55296
	v_exp_f32_e32 v96, v96
	v_exp_f32_e32 v128, v128
	v_exp_f32_e32 v98, v98
	v_exp_f32_e32 v130, v130
	v_pk_add_f32 v[210:211], v[212:213], v[210:211]
	v_mov_b32_e32 v212, v92
	v_mov_b32_e32 v213, v94
	v_mov_b32_e32 v214, v124
	v_mov_b32_e32 v215, v126
	v_sub_f32_e32 v97, v97, v170
	v_sub_f32_e32 v129, v129, v170
	v_sub_f32_e32 v99, v99, v170
	v_sub_f32_e32 v131, v131, v170
	v_pk_add_f32 v[212:213], v[212:213], v[214:215]
	v_exp_f32_e32 v97, v97
	v_exp_f32_e32 v129, v129
	v_exp_f32_e32 v99, v99
	v_exp_f32_e32 v131, v131
	v_pk_add_f32 v[208:209], v[212:213], v[208:209]
	v_mov_b32_e32 v212, v93
	v_mov_b32_e32 v213, v95
	v_mov_b32_e32 v214, v125
	v_mov_b32_e32 v215, v127
	v_pk_add_f32 v[212:213], v[212:213], v[214:215]
	v_mov_b32_e32 v214, v128
	v_pk_add_f32 v[210:211], v[212:213], v[210:211]
	v_mov_b32_e32 v212, v96
	v_mov_b32_e32 v213, v98
	v_mov_b32_e32 v215, v130
	v_pk_add_f32 v[212:213], v[212:213], v[214:215]
	v_mov_b32_e32 v214, v129
	v_pk_add_f32 v[208:209], v[212:213], v[208:209]
	v_mov_b32_e32 v212, v97
	v_mov_b32_e32 v213, v99
	v_mov_b32_e32 v215, v131
	v_pk_add_f32 v[212:213], v[212:213], v[214:215]
	v_cvt_pk_bf16_f32 v214, v120, v121
	v_pk_add_f32 v[210:211], v[212:213], v[210:211]
	v_cvt_pk_bf16_f32 v212, v116, v117
	v_pk_add_f32 v[208:209], v[208:209], v[210:211]
	v_cvt_pk_bf16_f32 v210, v88, v89
	v_add_f32_e32 v240, v208, v209
	v_cvt_pk_bf16_f32 v208, v84, v85
	v_cvt_pk_bf16_f32 v209, v86, v87
	v_cvt_pk_bf16_f32 v211, v90, v91
	v_cvt_pk_bf16_f32 v213, v118, v119
	v_cvt_pk_bf16_f32 v215, v122, v123
	v_cvt_pk_bf16_f32 v216, v92, v93
	v_cvt_pk_bf16_f32 v217, v94, v95
	v_cvt_pk_bf16_f32 v218, v96, v97
	v_cvt_pk_bf16_f32 v219, v98, v99
	v_cvt_pk_bf16_f32 v236, v124, v125
	v_cvt_pk_bf16_f32 v237, v126, v127
	v_cvt_pk_bf16_f32 v238, v128, v129
	v_cvt_pk_bf16_f32 v239, v130, v131
	s_setprio 1
	s_waitcnt lgkmcnt(8)
	v_mfma_f32_32x32x16_bf16 v[52:67], v[152:155], v[208:211], v[52:67]
	v_add_f32_e32 v167, v167, v240
	v_mfma_f32_32x32x16_bf16 v[36:51], v[148:151], v[208:211], v[36:51]
	v_mfma_f32_32x32x16_bf16 v[20:35], v[160:163], v[208:211], v[20:35]
	v_mfma_f32_32x32x16_bf16 v[4:19], v[156:159], v[208:211], v[4:19]
	s_setprio 0
	ds_read_b64_tr_b16 v[148:149], v200 offset:57344
	ds_read_b64_tr_b16 v[150:151], v201 offset:59392
	ds_read_b64_tr_b16 v[152:153], v202 offset:57344
	ds_read_b64_tr_b16 v[154:155], v203 offset:59392
	ds_read_b64_tr_b16 v[156:157], v204 offset:57344
	ds_read_b64_tr_b16 v[158:159], v205 offset:59392
	ds_read_b64_tr_b16 v[160:161], v206 offset:57344
	ds_read_b64_tr_b16 v[162:163], v207 offset:59392
	s_setprio 1
	s_waitcnt lgkmcnt(14)
	v_mfma_f32_32x32x16_bf16 v[52:67], v[220:223], v[216:219], v[52:67]
	s_waitcnt lgkmcnt(12)
	v_mfma_f32_32x32x16_bf16 v[36:51], v[224:227], v[216:219], v[36:51]
	s_waitcnt lgkmcnt(10)
	v_mfma_f32_32x32x16_bf16 v[20:35], v[228:231], v[216:219], v[20:35]
	s_waitcnt lgkmcnt(8)
	v_mfma_f32_32x32x16_bf16 v[4:19], v[232:235], v[216:219], v[4:19]
	s_setprio 0
	ds_read_b64_tr_b16 v[208:209], v200 offset:61440
	ds_read_b64_tr_b16 v[210:211], v201 offset:63488
	ds_read_b64_tr_b16 v[200:201], v202 offset:61440
	ds_read_b64_tr_b16 v[202:203], v203 offset:63488
	ds_read_b64_tr_b16 v[216:217], v204 offset:61440
	ds_read_b64_tr_b16 v[218:219], v205 offset:63488
	ds_read_b64_tr_b16 v[204:205], v206 offset:61440
	ds_read_b64_tr_b16 v[206:207], v207 offset:63488
	s_setprio 1
	s_waitcnt lgkmcnt(14)
	v_mfma_f32_32x32x16_bf16 v[52:67], v[148:151], v[212:215], v[52:67]
	s_waitcnt lgkmcnt(12)
	v_mfma_f32_32x32x16_bf16 v[36:51], v[152:155], v[212:215], v[36:51]
	s_waitcnt lgkmcnt(10)
	v_mfma_f32_32x32x16_bf16 v[20:35], v[156:159], v[212:215], v[20:35]
	s_waitcnt lgkmcnt(8)
	v_mfma_f32_32x32x16_bf16 v[4:19], v[160:163], v[212:215], v[4:19]
	s_setprio 0
	s_setprio 1
	s_waitcnt lgkmcnt(6)
	v_mfma_f32_32x32x16_bf16 v[52:67], v[208:211], v[236:239], v[52:67]
	s_waitcnt lgkmcnt(4)
	v_mfma_f32_32x32x16_bf16 v[36:51], v[200:203], v[236:239], v[36:51]
	s_waitcnt lgkmcnt(2)
	v_mfma_f32_32x32x16_bf16 v[20:35], v[216:219], v[236:239], v[20:35]
	s_waitcnt lgkmcnt(0)
	v_mfma_f32_32x32x16_bf16 v[4:19], v[204:207], v[236:239], v[4:19]
	s_setprio 0

; #define ATT_VREAD(dst, q_) do { const LAS char* vp_ = (const LAS char*)vb + (((q_) >> 1) * 32 + 16 * ((q_) & 1)) * VSTR; \
;         _Pragma("unroll") for (int d_ = 0; d_ < 4; ++d_) { dst[d_][0] = vtr(vp_ + voff[d_][0]); dst[d_][1] = vtr(vp_ + 8 * VSTR + voff[d_][1]); } } while (0)
;     ...
;         float mx = fmaxf(s0[0], s1[0]);
; #pragma unroll
;         for (int r = 1; r < 16; ++r) mx = fmaxf(mx, fmaxf(s0[r], s1[r]));
;         mx = fmaxf(mx, __shfl_xor(mx, 32));
;         const bool need = mx > mrun + 8.f;
;         if (__any(need)) { const float mnew = need ? mx : mrun, alpha = __builtin_amdgcn_exp2f(mrun - mnew); mrun = mnew; lrun *= alpha;
; #pragma unroll
;             for (int d = 0; d < 4; ++d)
; #pragma unroll
;                 for (int r = 0; r < 16; ++r) o[d][r] *= alpha; }
;     ...
;             if (wka) { vb = sa + KBUF + vlane; ATT_VREAD(vpre, 0); SM(wa0, wa1, a0, a1, pba);
.LBB0_3320:
	v_add_u32_e32 v146, s45, v195
	s_and_b64 vcc, exec, s[4:5]
	v_add_u32_e32 v201, v146, v171
	v_add_u32_e32 v202, v146, v188
	v_add_u32_e32 v203, v146, v189
	v_add_u32_e32 v204, v146, v190
	v_add_u32_e32 v205, v146, v191
	v_add_u32_e32 v206, v146, v192
	v_add_u32_e32 v207, v146, v193
	v_add_u32_e32 v208, v146, v194
	s_cbranch_vccnz .LBB0_3324
	v_max_f32_e32 v154, v99, v99
	v_max_f32_e32 v155, v67, v67
	v_max_f32_e32 v154, v155, v154
	v_max_f32_e32 v155, v100, v100
	v_max_f32_e32 v156, v68, v68
	v_max_f32_e32 v155, v156, v155
	v_max_f32_e32 v156, v101, v101
	v_max_f32_e32 v157, v69, v69
	v_max3_f32 v154, v66, v98, v154
	v_max_f32_e32 v156, v157, v156
	v_max3_f32 v154, v154, v155, v156
	v_max_f32_e32 v155, v102, v102
	v_max_f32_e32 v156, v70, v70
	v_max_f32_e32 v155, v156, v155
	v_max_f32_e32 v156, v103, v103
	v_max_f32_e32 v157, v71, v71
	v_max_f32_e32 v156, v157, v156
	v_max3_f32 v154, v154, v155, v156
	v_max_f32_e32 v155, v104, v104
	v_max_f32_e32 v156, v72, v72
	v_max_f32_e32 v155, v156, v155
	v_max_f32_e32 v156, v105, v105
	v_max_f32_e32 v157, v73, v73
	v_max_f32_e32 v156, v157, v156
	v_max3_f32 v154, v154, v155, v156
	v_max_f32_e32 v155, v106, v106
	v_max_f32_e32 v156, v74, v74
	v_max_f32_e32 v155, v156, v155
	v_max_f32_e32 v156, v107, v107
	v_max_f32_e32 v157, v75, v75
	v_max_f32_e32 v156, v157, v156
	v_max3_f32 v154, v154, v155, v156
	v_max_f32_e32 v155, v108, v108
	v_max_f32_e32 v156, v76, v76
	v_max_f32_e32 v155, v156, v155
	v_max_f32_e32 v156, v109, v109
	v_max_f32_e32 v157, v77, v77
	v_max_f32_e32 v156, v157, v156
	v_max3_f32 v154, v154, v155, v156
	v_max_f32_e32 v155, v110, v110
	v_max_f32_e32 v156, v78, v78
	v_max_f32_e32 v155, v156, v155
	v_max_f32_e32 v156, v111, v111
	v_max_f32_e32 v157, v79, v79
	v_max_f32_e32 v156, v157, v156
	v_max3_f32 v154, v154, v155, v156
	v_max_f32_e32 v155, v112, v112
	v_max_f32_e32 v156, v80, v80
	v_max_f32_e32 v155, v156, v155
	v_max_f32_e32 v156, v113, v113
	v_max_f32_e32 v157, v81, v81
	v_max_f32_e32 v156, v157, v156
	v_max3_f32 v209, v154, v155, v156
	s_waitcnt vmcnt(0)
	ds_read_b64_tr_b16 v[150:151], v201 offset:16384
	ds_read_b64_tr_b16 v[152:153], v202 offset:18432
	ds_read_b64_tr_b16 v[146:147], v203 offset:16384
	ds_read_b64_tr_b16 v[148:149], v204 offset:18432
	v_mov_b32_e32 v246, v209
	v_mov_b32_e32 v247, v209
	ds_read_b64_tr_b16 v[158:159], v205 offset:16384
	ds_read_b64_tr_b16 v[160:161], v206 offset:18432
	ds_read_b64_tr_b16 v[154:155], v207 offset:16384
	ds_read_b64_tr_b16 v[156:157], v208 offset:18432
	v_permlane32_swap_b32_e32 v246, v247
	v_max3_f32 v209, v209, v246, v247
	v_add_f32_e32 v210, 0x41000000, v170
	v_cmp_gt_f32_e32 vcc, v209, v210
	s_cbranch_vccz .LBB0_3323
	s_nop 0
	v_cndmask_b32_e32 v209, v170, v209, vcc
	v_sub_f32_e32 v170, v170, v209
	v_exp_f32_e32 v170, v170
	s_nop 0
	v_mul_f32_e32 v167, v167, v170
	v_pk_mul_f32 v[64:65], v[64:65], v[170:171] op_sel_hi:[1,0]
	v_pk_mul_f32 v[62:63], v[62:63], v[170:171] op_sel_hi:[1,0]
	v_pk_mul_f32 v[60:61], v[60:61], v[170:171] op_sel_hi:[1,0]
	v_pk_mul_f32 v[58:59], v[58:59], v[170:171] op_sel_hi:[1,0]
	v_pk_mul_f32 v[56:57], v[56:57], v[170:171] op_sel_hi:[1,0]
	v_pk_mul_f32 v[54:55], v[54:55], v[170:171] op_sel_hi:[1,0]
	v_pk_mul_f32 v[52:53], v[52:53], v[170:171] op_sel_hi:[1,0]
	v_pk_mul_f32 v[50:51], v[50:51], v[170:171] op_sel_hi:[1,0]
	v_pk_mul_f32 v[48:49], v[48:49], v[170:171] op_sel_hi:[1,0]
	v_pk_mul_f32 v[46:47], v[46:47], v[170:171] op_sel_hi:[1,0]
	v_pk_mul_f32 v[44:45], v[44:45], v[170:171] op_sel_hi:[1,0]
	v_pk_mul_f32 v[42:43], v[42:43], v[170:171] op_sel_hi:[1,0]
	v_pk_mul_f32 v[40:41], v[40:41], v[170:171] op_sel_hi:[1,0]
	v_pk_mul_f32 v[38:39], v[38:39], v[170:171] op_sel_hi:[1,0]
	v_pk_mul_f32 v[36:37], v[36:37], v[170:171] op_sel_hi:[1,0]
	v_pk_mul_f32 v[34:35], v[34:35], v[170:171] op_sel_hi:[1,0]
	v_pk_mul_f32 v[32:33], v[32:33], v[170:171] op_sel_hi:[1,0]
	v_pk_mul_f32 v[30:31], v[30:31], v[170:171] op_sel_hi:[1,0]
	v_pk_mul_f32 v[28:29], v[28:29], v[170:171] op_sel_hi:[1,0]
	v_pk_mul_f32 v[26:27], v[26:27], v[170:171] op_sel_hi:[1,0]
	v_pk_mul_f32 v[24:25], v[24:25], v[170:171] op_sel_hi:[1,0]
	v_pk_mul_f32 v[22:23], v[22:23], v[170:171] op_sel_hi:[1,0]
	v_pk_mul_f32 v[20:21], v[20:21], v[170:171] op_sel_hi:[1,0]
	v_pk_mul_f32 v[18:19], v[18:19], v[170:171] op_sel_hi:[1,0]
	v_pk_mul_f32 v[16:17], v[16:17], v[170:171] op_sel_hi:[1,0]
	v_pk_mul_f32 v[14:15], v[14:15], v[170:171] op_sel_hi:[1,0]
	v_pk_mul_f32 v[12:13], v[12:13], v[170:171] op_sel_hi:[1,0]
	v_pk_mul_f32 v[10:11], v[10:11], v[170:171] op_sel_hi:[1,0]
	v_pk_mul_f32 v[8:9], v[8:9], v[170:171] op_sel_hi:[1,0]
	v_pk_mul_f32 v[6:7], v[6:7], v[170:171] op_sel_hi:[1,0]
	v_pk_mul_f32 v[4:5], v[4:5], v[170:171] op_sel_hi:[1,0]
	v_pk_mul_f32 v[2:3], v[2:3], v[170:171] op_sel_hi:[1,0]
	v_mov_b32_e32 v170, v209
; __device__ __forceinline__ unsigned cvtpk(float lo, float hi) { typedef __bf16 b2 __attribute__((ext_vector_type(2))); f32x2 v = {lo, hi}; b2 b = __builtin_convertvector(v, b2); return __builtin_bit_cast(unsigned, b); }
; __device__ __forceinline__ int crow(int r, int hi) { return (r & 3) + 8 * (r >> 2) + 4 * hi; }
; #define ATT_VREAD(dst, q_) do { const LAS char* vp_ = (const LAS char*)vb + (((q_) >> 1) * 32 + 16 * ((q_) & 1)) * VSTR; \
;         _Pragma("unroll") for (int d_ = 0; d_ < 4; ++d_) { dst[d_][0] = vtr(vp_ + voff[d_][0]); dst[d_][1] = vtr(vp_ + 8 * VSTR + voff[d_][1]); } } while (0)
;     ...
;         float rsa[4] = {0.f, 0.f, 0.f, 0.f};
; #pragma unroll
;         for (int r = 0; r < 16; ++r) { float p0 = __builtin_amdgcn_exp2f(s0[r] - mrun), p1 = __builtin_amdgcn_exp2f(s1[r] - mrun);
;             if (LAYER == 1) { const int kv = crow(r, hi); p0 = ((w0 >> kv) & 1u) ? p0 : 0.f; p1 = ((w1 >> kv) & 1u) ? p1 : 0.f; }
;             s0[r] = p0; s1[r] = p1; rsa[r & 3] += p0 + p1; }
;         lrun += (rsa[0] + rsa[1]) + (rsa[2] + rsa[3]);
; #pragma unroll
;         for (int s = 0; s < 2; ++s) {
;             v4u x; x.x = cvtpk(s0[8 * s + 0], s0[8 * s + 1]); x.y = cvtpk(s0[8 * s + 2], s0[8 * s + 3]); x.z = cvtpk(s0[8 * s + 4], s0[8 * s + 5]); x.w = cvtpk(s0[8 * s + 6], s0[8 * s + 7]); pb[0][s] = __builtin_bit_cast(bf16x8, x);
;             v4u y; y.x = cvtpk(s1[8 * s + 0], s1[8 * s + 1]); y.y = cvtpk(s1[8 * s + 2], s1[8 * s + 3]); y.z = cvtpk(s1[8 * s + 4], s1[8 * s + 5]); y.w = cvtpk(s1[8 * s + 6], s1[8 * s + 7]); pb[1][s] = __builtin_bit_cast(bf16x8, y); }
;     ...
;             if (wka) { vb = sa + KBUF + vlane; ATT_VREAD(vpre, 0); SM(wa0, wa1, a0, a1, pba);
;                 ATT_VREAD(va, 1); __builtin_amdgcn_s_setprio(1); ATT_PV(vpre, pba, 0); __builtin_amdgcn_s_setprio(0);
;                 ATT_VREAD(vbb, 2); __builtin_amdgcn_s_setprio(1); ATT_PV(va, pba, 1); __builtin_amdgcn_s_setprio(0);
;                 ATT_VREAD(va, 3); __builtin_amdgcn_s_setprio(1); ATT_PV(vbb, pba, 2); __builtin_amdgcn_s_setprio(0);
;                 __builtin_amdgcn_s_setprio(1); ATT_PV(va, pba, 3); __builtin_amdgcn_s_setprio(0); }
.LBB0_3323:
	v_sub_f32_e32 v66, v66, v170
	v_sub_f32_e32 v98, v98, v170
	v_sub_f32_e32 v68, v68, v170
	v_sub_f32_e32 v100, v100, v170
	v_exp_f32_e32 v66, v66
	v_exp_f32_e32 v98, v98
	v_sub_f32_e32 v67, v67, v170
	v_sub_f32_e32 v99, v99, v170
	v_exp_f32_e32 v68, v68
	v_exp_f32_e32 v100, v100
	v_sub_f32_e32 v69, v69, v170
	v_sub_f32_e32 v101, v101, v170
	v_exp_f32_e32 v67, v67
	v_exp_f32_e32 v99, v99
	v_exp_f32_e32 v69, v69
	v_exp_f32_e32 v101, v101
	v_sub_f32_e32 v70, v70, v170
	v_sub_f32_e32 v102, v102, v170
	v_sub_f32_e32 v72, v72, v170
	v_sub_f32_e32 v104, v104, v170
	v_exp_f32_e32 v70, v70
	v_exp_f32_e32 v102, v102
	v_exp_f32_e32 v72, v72
	v_exp_f32_e32 v104, v104
	v_sub_f32_e32 v71, v71, v170
	v_sub_f32_e32 v103, v103, v170
	v_sub_f32_e32 v73, v73, v170
	v_sub_f32_e32 v105, v105, v170
	v_exp_f32_e32 v71, v71
	v_exp_f32_e32 v103, v103
	v_exp_f32_e32 v73, v73
	v_exp_f32_e32 v105, v105
	v_mov_b32_e32 v210, v66
	v_mov_b32_e32 v211, v68
	v_mov_b32_e32 v212, v98
	v_mov_b32_e32 v213, v100
	v_sub_f32_e32 v74, v74, v170
	v_sub_f32_e32 v106, v106, v170
	v_sub_f32_e32 v76, v76, v170
	v_sub_f32_e32 v108, v108, v170
	v_pk_add_f32 v[210:211], v[210:211], v[212:213]
	v_mov_b32_e32 v212, v67
	v_mov_b32_e32 v213, v69
	v_mov_b32_e32 v214, v99
	v_mov_b32_e32 v215, v101
	v_exp_f32_e32 v74, v74
	v_exp_f32_e32 v106, v106
	v_exp_f32_e32 v76, v76
	v_exp_f32_e32 v108, v108
	v_pk_add_f32 v[212:213], v[212:213], v[214:215]
	v_mov_b32_e32 v214, v70
	v_mov_b32_e32 v215, v72
	v_mov_b32_e32 v216, v102
	v_mov_b32_e32 v217, v104
	v_sub_f32_e32 v75, v75, v170
	v_sub_f32_e32 v107, v107, v170
	v_sub_f32_e32 v77, v77, v170
	v_sub_f32_e32 v109, v109, v170
	v_pk_add_f32 v[210:211], v[210:211], 0 op_sel_hi:[1,0]
	v_pk_add_f32 v[214:215], v[214:215], v[216:217]
	v_exp_f32_e32 v75, v75
	v_exp_f32_e32 v107, v107
	v_exp_f32_e32 v77, v77
	v_exp_f32_e32 v109, v109
	v_pk_add_f32 v[210:211], v[214:215], v[210:211]
	v_mov_b32_e32 v214, v71
	v_mov_b32_e32 v215, v73
	v_mov_b32_e32 v216, v103
	v_mov_b32_e32 v217, v105
	v_sub_f32_e32 v78, v78, v170
	v_sub_f32_e32 v110, v110, v170
	v_sub_f32_e32 v80, v80, v170
	v_sub_f32_e32 v112, v112, v170
	v_pk_add_f32 v[212:213], v[212:213], 0 op_sel_hi:[1,0]
	v_pk_add_f32 v[214:215], v[214:215], v[216:217]
	ds_read_b64_tr_b16 v[222:223], v201 offset:20480
	ds_read_b64_tr_b16 v[224:225], v202 offset:22528
	ds_read_b64_tr_b16 v[226:227], v203 offset:20480
	ds_read_b64_tr_b16 v[228:229], v204 offset:22528
	ds_read_b64_tr_b16 v[230:231], v205 offset:20480
	ds_read_b64_tr_b16 v[232:233], v206 offset:22528
	ds_read_b64_tr_b16 v[234:235], v207 offset:20480
	ds_read_b64_tr_b16 v[236:237], v208 offset:22528
	v_exp_f32_e32 v78, v78
	v_exp_f32_e32 v110, v110
	v_exp_f32_e32 v80, v80
	v_exp_f32_e32 v112, v112
	v_pk_add_f32 v[212:213], v[214:215], v[212:213]
	v_mov_b32_e32 v214, v74
	v_mov_b32_e32 v215, v76
	v_mov_b32_e32 v216, v106
	v_mov_b32_e32 v217, v108
	v_sub_f32_e32 v79, v79, v170
	v_sub_f32_e32 v111, v111, v170
	v_sub_f32_e32 v81, v81, v170
	v_sub_f32_e32 v113, v113, v170
	v_pk_add_f32 v[214:215], v[214:215], v[216:217]
	v_exp_f32_e32 v79, v79
	v_exp_f32_e32 v111, v111
	v_exp_f32_e32 v81, v81
	v_exp_f32_e32 v113, v113
	v_pk_add_f32 v[210:211], v[214:215], v[210:211]
	v_mov_b32_e32 v214, v75
	v_mov_b32_e32 v215, v77
	v_mov_b32_e32 v216, v107
	v_mov_b32_e32 v217, v109
	v_pk_add_f32 v[214:215], v[214:215], v[216:217]
	v_mov_b32_e32 v216, v110
	v_pk_add_f32 v[212:213], v[214:215], v[212:213]
	v_mov_b32_e32 v214, v78
	v_mov_b32_e32 v215, v80
	v_mov_b32_e32 v217, v112
	v_pk_add_f32 v[214:215], v[214:215], v[216:217]
	v_mov_b32_e32 v216, v111
	v_pk_add_f32 v[210:211], v[214:215], v[210:211]
	v_mov_b32_e32 v214, v79
	v_mov_b32_e32 v215, v81
	v_mov_b32_e32 v217, v113
	v_pk_add_f32 v[214:215], v[214:215], v[216:217]
	v_cvt_pk_bf16_f32 v216, v102, v103
	v_pk_add_f32 v[212:213], v[214:215], v[212:213]
	v_cvt_pk_bf16_f32 v214, v98, v99
	v_pk_add_f32 v[210:211], v[210:211], v[212:213]
	v_cvt_pk_bf16_f32 v212, v70, v71
	v_add_f32_e32 v209, v210, v211
	v_cvt_pk_bf16_f32 v210, v66, v67
	v_cvt_pk_bf16_f32 v211, v68, v69
	v_cvt_pk_bf16_f32 v213, v72, v73
	v_cvt_pk_bf16_f32 v215, v100, v101
	v_cvt_pk_bf16_f32 v217, v104, v105
	v_cvt_pk_bf16_f32 v218, v74, v75
	v_cvt_pk_bf16_f32 v219, v76, v77
	v_cvt_pk_bf16_f32 v220, v78, v79
	v_cvt_pk_bf16_f32 v221, v80, v81
	v_cvt_pk_bf16_f32 v238, v106, v107
	v_cvt_pk_bf16_f32 v239, v108, v109
	v_cvt_pk_bf16_f32 v240, v110, v111
	v_cvt_pk_bf16_f32 v241, v112, v113
	s_setprio 1
	s_waitcnt lgkmcnt(8)
	v_mfma_f32_32x32x16_bf16 v[50:65], v[150:153], v[210:213], v[50:65]
	v_add_f32_e32 v167, v167, v209
	v_mfma_f32_32x32x16_bf16 v[34:49], v[146:149], v[210:213], v[34:49]
	v_mfma_f32_32x32x16_bf16 v[18:33], v[158:161], v[210:213], v[18:33]
	v_mfma_f32_32x32x16_bf16 v[2:17], v[154:157], v[210:213], v[2:17]
	s_setprio 0
	ds_read_b64_tr_b16 v[146:147], v201 offset:24576
	ds_read_b64_tr_b16 v[148:149], v202 offset:26624
	ds_read_b64_tr_b16 v[150:151], v203 offset:24576
	ds_read_b64_tr_b16 v[152:153], v204 offset:26624
	ds_read_b64_tr_b16 v[154:155], v205 offset:24576
	ds_read_b64_tr_b16 v[156:157], v206 offset:26624
	ds_read_b64_tr_b16 v[158:159], v207 offset:24576
	ds_read_b64_tr_b16 v[160:161], v208 offset:26624
	s_setprio 1
	s_waitcnt lgkmcnt(14)
	v_mfma_f32_32x32x16_bf16 v[50:65], v[222:225], v[218:221], v[50:65]
	s_waitcnt lgkmcnt(12)
	v_mfma_f32_32x32x16_bf16 v[34:49], v[226:229], v[218:221], v[34:49]
	s_waitcnt lgkmcnt(10)
	v_mfma_f32_32x32x16_bf16 v[18:33], v[230:233], v[218:221], v[18:33]
	s_waitcnt lgkmcnt(8)
	v_mfma_f32_32x32x16_bf16 v[2:17], v[234:237], v[218:221], v[2:17]
	s_setprio 0
	ds_read_b64_tr_b16 v[210:211], v201 offset:28672
	ds_read_b64_tr_b16 v[212:213], v202 offset:30720
	ds_read_b64_tr_b16 v[218:219], v203 offset:28672
	ds_read_b64_tr_b16 v[220:221], v204 offset:30720
	ds_read_b64_tr_b16 v[222:223], v205 offset:28672
	ds_read_b64_tr_b16 v[224:225], v206 offset:30720
	ds_read_b64_tr_b16 v[226:227], v207 offset:28672
	ds_read_b64_tr_b16 v[228:229], v208 offset:30720
	s_setprio 1
	s_waitcnt lgkmcnt(14)
	v_mfma_f32_32x32x16_bf16 v[50:65], v[146:149], v[214:217], v[50:65]
	s_waitcnt lgkmcnt(12)
	v_mfma_f32_32x32x16_bf16 v[34:49], v[150:153], v[214:217], v[34:49]
	s_waitcnt lgkmcnt(10)
	v_mfma_f32_32x32x16_bf16 v[18:33], v[154:157], v[214:217], v[18:33]
	s_waitcnt lgkmcnt(8)
	v_mfma_f32_32x32x16_bf16 v[2:17], v[158:161], v[214:217], v[2:17]
	s_setprio 0
	s_setprio 1
	s_waitcnt lgkmcnt(6)
	v_mfma_f32_32x32x16_bf16 v[50:65], v[210:213], v[238:241], v[50:65]
	s_waitcnt lgkmcnt(4)
	v_mfma_f32_32x32x16_bf16 v[34:49], v[218:221], v[238:241], v[34:49]
	s_waitcnt lgkmcnt(2)
	v_mfma_f32_32x32x16_bf16 v[18:33], v[222:225], v[238:241], v[18:33]
	s_waitcnt lgkmcnt(0)
	v_mfma_f32_32x32x16_bf16 v[2:17], v[226:229], v[238:241], v[2:17]
	s_setprio 0
; #define ATT_VREAD(dst, q_) do { const LAS char* vp_ = (const LAS char*)vb + (((q_) >> 1) * 32 + 16 * ((q_) & 1)) * VSTR; \
;         _Pragma("unroll") for (int d_ = 0; d_ < 4; ++d_) { dst[d_][0] = vtr(vp_ + voff[d_][0]); dst[d_][1] = vtr(vp_ + 8 * VSTR + voff[d_][1]); } } while (0)
;     ...
;         float mx = fmaxf(s0[0], s1[0]);
; #pragma unroll
;         for (int r = 1; r < 16; ++r) mx = fmaxf(mx, fmaxf(s0[r], s1[r]));
;         mx = fmaxf(mx, __shfl_xor(mx, 32));
;         const bool need = mx > mrun + 8.f;
;         if (__any(need)) { const float mnew = need ? mx : mrun, alpha = __builtin_amdgcn_exp2f(mrun - mnew); mrun = mnew; lrun *= alpha;
; #pragma unroll
;             for (int d = 0; d < 4; ++d)
; #pragma unroll
;                 for (int r = 0; r < 16; ++r) o[d][r] *= alpha; }
;     ...
;             if (wkb) { vb = sbb + KBUF + vlane; ATT_VREAD(vpre, 0); SM(wb0, wb1, b0, b1, pbb);
.LBB0_3324:
	s_and_b64 vcc, exec, s[2:3]
	s_cbranch_vccnz .LBB0_3328
	v_max_f32_e32 v154, v115, v115
	v_max_f32_e32 v155, v83, v83
	v_max_f32_e32 v154, v155, v154
	v_max_f32_e32 v155, v116, v116
	v_max_f32_e32 v156, v84, v84
	v_max_f32_e32 v155, v156, v155
	v_max_f32_e32 v156, v117, v117
	v_max_f32_e32 v157, v85, v85
	v_max3_f32 v154, v82, v114, v154
	v_max_f32_e32 v156, v157, v156
	v_max3_f32 v154, v154, v155, v156
	v_max_f32_e32 v155, v118, v118
	v_max_f32_e32 v156, v86, v86
	v_max_f32_e32 v155, v156, v155
	v_max_f32_e32 v156, v119, v119
	v_max_f32_e32 v157, v87, v87
	v_max_f32_e32 v156, v157, v156
	v_max3_f32 v154, v154, v155, v156
	v_max_f32_e32 v155, v120, v120
	v_max_f32_e32 v156, v88, v88
	v_max_f32_e32 v155, v156, v155
	v_max_f32_e32 v156, v121, v121
	v_max_f32_e32 v157, v89, v89
	v_max_f32_e32 v156, v157, v156
	v_max3_f32 v154, v154, v155, v156
	v_max_f32_e32 v155, v122, v122
	v_max_f32_e32 v156, v90, v90
	v_max_f32_e32 v155, v156, v155
	v_max_f32_e32 v156, v123, v123
	v_max_f32_e32 v157, v91, v91
	v_max_f32_e32 v156, v157, v156
	v_max3_f32 v154, v154, v155, v156
	v_max_f32_e32 v155, v124, v124
	v_max_f32_e32 v156, v92, v92
	v_max_f32_e32 v155, v156, v155
	v_max_f32_e32 v156, v125, v125
	v_max_f32_e32 v157, v93, v93
	v_max_f32_e32 v156, v157, v156
	v_max3_f32 v154, v154, v155, v156
	v_max_f32_e32 v155, v126, v126
	v_max_f32_e32 v156, v94, v94
	v_max_f32_e32 v155, v156, v155
	v_max_f32_e32 v156, v127, v127
	v_max_f32_e32 v157, v95, v95
	v_max_f32_e32 v156, v157, v156
	v_max3_f32 v154, v154, v155, v156
	v_max_f32_e32 v155, v128, v128
	v_max_f32_e32 v156, v96, v96
	v_max_f32_e32 v155, v156, v155
	v_max_f32_e32 v156, v129, v129
	v_max_f32_e32 v157, v97, v97
	v_max_f32_e32 v156, v157, v156
	v_max3_f32 v209, v154, v155, v156
	s_waitcnt vmcnt(0)
	ds_read_b64_tr_b16 v[150:151], v201 offset:49152
	ds_read_b64_tr_b16 v[152:153], v202 offset:51200
	ds_read_b64_tr_b16 v[146:147], v203 offset:49152
	ds_read_b64_tr_b16 v[148:149], v204 offset:51200
	v_mov_b32_e32 v246, v209
	v_mov_b32_e32 v247, v209
	ds_read_b64_tr_b16 v[158:159], v205 offset:49152
	ds_read_b64_tr_b16 v[160:161], v206 offset:51200
	ds_read_b64_tr_b16 v[154:155], v207 offset:49152
	ds_read_b64_tr_b16 v[156:157], v208 offset:51200
	v_permlane32_swap_b32_e32 v246, v247
	v_max3_f32 v209, v209, v246, v247
	v_add_f32_e32 v210, 0x41000000, v170
	v_cmp_gt_f32_e32 vcc, v209, v210
	s_cbranch_vccz .LBB0_3327
	s_nop 0
	v_cndmask_b32_e32 v209, v170, v209, vcc
	v_sub_f32_e32 v170, v170, v209
	v_exp_f32_e32 v170, v170
	s_nop 0
	v_mul_f32_e32 v167, v167, v170
	v_pk_mul_f32 v[64:65], v[64:65], v[170:171] op_sel_hi:[1,0]
	v_pk_mul_f32 v[62:63], v[62:63], v[170:171] op_sel_hi:[1,0]
	v_pk_mul_f32 v[60:61], v[60:61], v[170:171] op_sel_hi:[1,0]
	v_pk_mul_f32 v[58:59], v[58:59], v[170:171] op_sel_hi:[1,0]
	v_pk_mul_f32 v[56:57], v[56:57], v[170:171] op_sel_hi:[1,0]
	v_pk_mul_f32 v[54:55], v[54:55], v[170:171] op_sel_hi:[1,0]
	v_pk_mul_f32 v[52:53], v[52:53], v[170:171] op_sel_hi:[1,0]
	v_pk_mul_f32 v[50:51], v[50:51], v[170:171] op_sel_hi:[1,0]
	v_pk_mul_f32 v[48:49], v[48:49], v[170:171] op_sel_hi:[1,0]
	v_pk_mul_f32 v[46:47], v[46:47], v[170:171] op_sel_hi:[1,0]
	v_pk_mul_f32 v[44:45], v[44:45], v[170:171] op_sel_hi:[1,0]
	v_pk_mul_f32 v[42:43], v[42:43], v[170:171] op_sel_hi:[1,0]
	v_pk_mul_f32 v[40:41], v[40:41], v[170:171] op_sel_hi:[1,0]
	v_pk_mul_f32 v[38:39], v[38:39], v[170:171] op_sel_hi:[1,0]
	v_pk_mul_f32 v[36:37], v[36:37], v[170:171] op_sel_hi:[1,0]
	v_pk_mul_f32 v[34:35], v[34:35], v[170:171] op_sel_hi:[1,0]
	v_pk_mul_f32 v[32:33], v[32:33], v[170:171] op_sel_hi:[1,0]
	v_pk_mul_f32 v[30:31], v[30:31], v[170:171] op_sel_hi:[1,0]
	v_pk_mul_f32 v[28:29], v[28:29], v[170:171] op_sel_hi:[1,0]
	v_pk_mul_f32 v[26:27], v[26:27], v[170:171] op_sel_hi:[1,0]
	v_pk_mul_f32 v[24:25], v[24:25], v[170:171] op_sel_hi:[1,0]
	v_pk_mul_f32 v[22:23], v[22:23], v[170:171] op_sel_hi:[1,0]
	v_pk_mul_f32 v[20:21], v[20:21], v[170:171] op_sel_hi:[1,0]
	v_pk_mul_f32 v[18:19], v[18:19], v[170:171] op_sel_hi:[1,0]
	v_pk_mul_f32 v[16:17], v[16:17], v[170:171] op_sel_hi:[1,0]
	v_pk_mul_f32 v[14:15], v[14:15], v[170:171] op_sel_hi:[1,0]
	v_pk_mul_f32 v[12:13], v[12:13], v[170:171] op_sel_hi:[1,0]
	v_pk_mul_f32 v[10:11], v[10:11], v[170:171] op_sel_hi:[1,0]
	v_pk_mul_f32 v[8:9], v[8:9], v[170:171] op_sel_hi:[1,0]
	v_pk_mul_f32 v[6:7], v[6:7], v[170:171] op_sel_hi:[1,0]
	v_pk_mul_f32 v[4:5], v[4:5], v[170:171] op_sel_hi:[1,0]
	v_pk_mul_f32 v[2:3], v[2:3], v[170:171] op_sel_hi:[1,0]
	v_mov_b32_e32 v170, v209
; __device__ __forceinline__ unsigned cvtpk(float lo, float hi) { typedef __bf16 b2 __attribute__((ext_vector_type(2))); f32x2 v = {lo, hi}; b2 b = __builtin_convertvector(v, b2); return __builtin_bit_cast(unsigned, b); }
; __device__ __forceinline__ int crow(int r, int hi) { return (r & 3) + 8 * (r >> 2) + 4 * hi; }
; #define ATT_VREAD(dst, q_) do { const LAS char* vp_ = (const LAS char*)vb + (((q_) >> 1) * 32 + 16 * ((q_) & 1)) * VSTR; \
;         _Pragma("unroll") for (int d_ = 0; d_ < 4; ++d_) { dst[d_][0] = vtr(vp_ + voff[d_][0]); dst[d_][1] = vtr(vp_ + 8 * VSTR + voff[d_][1]); } } while (0)
;     ...
;         float rsa[4] = {0.f, 0.f, 0.f, 0.f};
; #pragma unroll
;         for (int r = 0; r < 16; ++r) { float p0 = __builtin_amdgcn_exp2f(s0[r] - mrun), p1 = __builtin_amdgcn_exp2f(s1[r] - mrun);
;             if (LAYER == 1) { const int kv = crow(r, hi); p0 = ((w0 >> kv) & 1u) ? p0 : 0.f; p1 = ((w1 >> kv) & 1u) ? p1 : 0.f; }
;             s0[r] = p0; s1[r] = p1; rsa[r & 3] += p0 + p1; }
;         lrun += (rsa[0] + rsa[1]) + (rsa[2] + rsa[3]);
; #pragma unroll
;         for (int s = 0; s < 2; ++s) {
;             v4u x; x.x = cvtpk(s0[8 * s + 0], s0[8 * s + 1]); x.y = cvtpk(s0[8 * s + 2], s0[8 * s + 3]); x.z = cvtpk(s0[8 * s + 4], s0[8 * s + 5]); x.w = cvtpk(s0[8 * s + 6], s0[8 * s + 7]); pb[0][s] = __builtin_bit_cast(bf16x8, x);
;             v4u y; y.x = cvtpk(s1[8 * s + 0], s1[8 * s + 1]); y.y = cvtpk(s1[8 * s + 2], s1[8 * s + 3]); y.z = cvtpk(s1[8 * s + 4], s1[8 * s + 5]); y.w = cvtpk(s1[8 * s + 6], s1[8 * s + 7]); pb[1][s] = __builtin_bit_cast(bf16x8, y); }
;     ...
;             if (wkb) { vb = sbb + KBUF + vlane; ATT_VREAD(vpre, 0); SM(wb0, wb1, b0, b1, pbb);
;                 ATT_VREAD(va, 1); __builtin_amdgcn_s_setprio(1); ATT_PV(vpre, pbb, 0); __builtin_amdgcn_s_setprio(0);
;                 ATT_VREAD(vbb, 2); __builtin_amdgcn_s_setprio(1); ATT_PV(va, pbb, 1); __builtin_amdgcn_s_setprio(0);
;                 ATT_VREAD(va, 3); __builtin_amdgcn_s_setprio(1); ATT_PV(vbb, pbb, 2); __builtin_amdgcn_s_setprio(0);
;                 __builtin_amdgcn_s_setprio(1); ATT_PV(va, pbb, 3); __builtin_amdgcn_s_setprio(0); }
.LBB0_3327:
	v_sub_f32_e32 v82, v82, v170
	v_sub_f32_e32 v114, v114, v170
	v_sub_f32_e32 v84, v84, v170
	v_sub_f32_e32 v116, v116, v170
	v_exp_f32_e32 v82, v82
	v_exp_f32_e32 v114, v114
	v_sub_f32_e32 v83, v83, v170
	v_sub_f32_e32 v115, v115, v170
	v_exp_f32_e32 v84, v84
	v_exp_f32_e32 v116, v116
	v_sub_f32_e32 v85, v85, v170
	v_sub_f32_e32 v117, v117, v170
	v_exp_f32_e32 v83, v83
	v_exp_f32_e32 v115, v115
	v_exp_f32_e32 v85, v85
	v_exp_f32_e32 v117, v117
	v_sub_f32_e32 v86, v86, v170
	v_sub_f32_e32 v118, v118, v170
	v_sub_f32_e32 v88, v88, v170
	v_sub_f32_e32 v120, v120, v170
	v_exp_f32_e32 v86, v86
	v_exp_f32_e32 v118, v118
	v_exp_f32_e32 v88, v88
	v_exp_f32_e32 v120, v120
	v_sub_f32_e32 v87, v87, v170
	v_sub_f32_e32 v119, v119, v170
	v_sub_f32_e32 v89, v89, v170
	v_sub_f32_e32 v121, v121, v170
	v_exp_f32_e32 v87, v87
	v_exp_f32_e32 v119, v119
	v_exp_f32_e32 v89, v89
	v_exp_f32_e32 v121, v121
	v_mov_b32_e32 v210, v82
	v_mov_b32_e32 v211, v84
	v_mov_b32_e32 v212, v114
	v_mov_b32_e32 v213, v116
	v_sub_f32_e32 v90, v90, v170
	v_sub_f32_e32 v122, v122, v170
	v_sub_f32_e32 v92, v92, v170
	v_sub_f32_e32 v124, v124, v170
	v_pk_add_f32 v[210:211], v[210:211], v[212:213]
	v_mov_b32_e32 v212, v83
	v_mov_b32_e32 v213, v85
	v_mov_b32_e32 v214, v115
	v_mov_b32_e32 v215, v117
	v_exp_f32_e32 v90, v90
	v_exp_f32_e32 v122, v122
	v_exp_f32_e32 v92, v92
	v_exp_f32_e32 v124, v124
	v_pk_add_f32 v[212:213], v[212:213], v[214:215]
	v_mov_b32_e32 v214, v86
	v_mov_b32_e32 v215, v88
	v_mov_b32_e32 v216, v118
	v_mov_b32_e32 v217, v120
	v_sub_f32_e32 v91, v91, v170
	v_sub_f32_e32 v123, v123, v170
	v_sub_f32_e32 v93, v93, v170
	v_sub_f32_e32 v125, v125, v170
	v_pk_add_f32 v[210:211], v[210:211], 0 op_sel_hi:[1,0]
	v_pk_add_f32 v[214:215], v[214:215], v[216:217]
	v_exp_f32_e32 v91, v91
	v_exp_f32_e32 v123, v123
	v_exp_f32_e32 v93, v93
	v_exp_f32_e32 v125, v125
	v_pk_add_f32 v[210:211], v[214:215], v[210:211]
	v_mov_b32_e32 v214, v87
	v_mov_b32_e32 v215, v89
	v_mov_b32_e32 v216, v119
	v_mov_b32_e32 v217, v121
	v_sub_f32_e32 v94, v94, v170
	v_sub_f32_e32 v126, v126, v170
	v_sub_f32_e32 v96, v96, v170
	v_sub_f32_e32 v128, v128, v170
	v_pk_add_f32 v[212:213], v[212:213], 0 op_sel_hi:[1,0]
	v_pk_add_f32 v[214:215], v[214:215], v[216:217]
	ds_read_b64_tr_b16 v[222:223], v201 offset:53248
	ds_read_b64_tr_b16 v[224:225], v202 offset:55296
	ds_read_b64_tr_b16 v[226:227], v203 offset:53248
	ds_read_b64_tr_b16 v[228:229], v204 offset:55296
	ds_read_b64_tr_b16 v[230:231], v205 offset:53248
	ds_read_b64_tr_b16 v[232:233], v206 offset:55296
	ds_read_b64_tr_b16 v[234:235], v207 offset:53248
	ds_read_b64_tr_b16 v[236:237], v208 offset:55296
	v_exp_f32_e32 v94, v94
	v_exp_f32_e32 v126, v126
	v_exp_f32_e32 v96, v96
	v_exp_f32_e32 v128, v128
	v_pk_add_f32 v[212:213], v[214:215], v[212:213]
	v_mov_b32_e32 v214, v90
	v_mov_b32_e32 v215, v92
	v_mov_b32_e32 v216, v122
	v_mov_b32_e32 v217, v124
	v_sub_f32_e32 v95, v95, v170
	v_sub_f32_e32 v127, v127, v170
	v_sub_f32_e32 v97, v97, v170
	v_sub_f32_e32 v129, v129, v170
	v_pk_add_f32 v[214:215], v[214:215], v[216:217]
	v_exp_f32_e32 v95, v95
	v_exp_f32_e32 v127, v127
	v_exp_f32_e32 v97, v97
	v_exp_f32_e32 v129, v129
	v_pk_add_f32 v[210:211], v[214:215], v[210:211]
	v_mov_b32_e32 v214, v91
	v_mov_b32_e32 v215, v93
	v_mov_b32_e32 v216, v123
	v_mov_b32_e32 v217, v125
	v_pk_add_f32 v[214:215], v[214:215], v[216:217]
	v_mov_b32_e32 v216, v126
	v_pk_add_f32 v[212:213], v[214:215], v[212:213]
	v_mov_b32_e32 v214, v94
	v_mov_b32_e32 v215, v96
	v_mov_b32_e32 v217, v128
	v_pk_add_f32 v[214:215], v[214:215], v[216:217]
	v_mov_b32_e32 v216, v127
	v_pk_add_f32 v[210:211], v[214:215], v[210:211]
	v_mov_b32_e32 v214, v95
	v_mov_b32_e32 v215, v97
	v_mov_b32_e32 v217, v129
	v_pk_add_f32 v[214:215], v[214:215], v[216:217]
	v_cvt_pk_bf16_f32 v216, v118, v119
	v_pk_add_f32 v[212:213], v[214:215], v[212:213]
	v_cvt_pk_bf16_f32 v214, v114, v115
	v_pk_add_f32 v[210:211], v[210:211], v[212:213]
	v_cvt_pk_bf16_f32 v212, v86, v87
	v_add_f32_e32 v209, v210, v211
	v_cvt_pk_bf16_f32 v210, v82, v83
	v_cvt_pk_bf16_f32 v211, v84, v85
	v_cvt_pk_bf16_f32 v213, v88, v89
	v_cvt_pk_bf16_f32 v215, v116, v117
	v_cvt_pk_bf16_f32 v217, v120, v121
	v_cvt_pk_bf16_f32 v218, v90, v91
	v_cvt_pk_bf16_f32 v219, v92, v93
	v_cvt_pk_bf16_f32 v220, v94, v95
	v_cvt_pk_bf16_f32 v221, v96, v97
	v_cvt_pk_bf16_f32 v238, v122, v123
	v_cvt_pk_bf16_f32 v239, v124, v125
	v_cvt_pk_bf16_f32 v240, v126, v127
	v_cvt_pk_bf16_f32 v241, v128, v129
	s_setprio 1
	s_waitcnt lgkmcnt(8)
	v_mfma_f32_32x32x16_bf16 v[50:65], v[150:153], v[210:213], v[50:65]
	v_add_f32_e32 v167, v167, v209
	v_mfma_f32_32x32x16_bf16 v[34:49], v[146:149], v[210:213], v[34:49]
	v_mfma_f32_32x32x16_bf16 v[18:33], v[158:161], v[210:213], v[18:33]
	v_mfma_f32_32x32x16_bf16 v[2:17], v[154:157], v[210:213], v[2:17]
	s_setprio 0
	ds_read_b64_tr_b16 v[146:147], v201 offset:57344
	ds_read_b64_tr_b16 v[148:149], v202 offset:59392
	ds_read_b64_tr_b16 v[150:151], v203 offset:57344
	ds_read_b64_tr_b16 v[152:153], v204 offset:59392
	ds_read_b64_tr_b16 v[154:155], v205 offset:57344
	ds_read_b64_tr_b16 v[156:157], v206 offset:59392
	ds_read_b64_tr_b16 v[158:159], v207 offset:57344
	ds_read_b64_tr_b16 v[160:161], v208 offset:59392
	s_setprio 1
	s_waitcnt lgkmcnt(14)
	v_mfma_f32_32x32x16_bf16 v[50:65], v[222:225], v[218:221], v[50:65]
	s_waitcnt lgkmcnt(12)
	v_mfma_f32_32x32x16_bf16 v[34:49], v[226:229], v[218:221], v[34:49]
	s_waitcnt lgkmcnt(10)
	v_mfma_f32_32x32x16_bf16 v[18:33], v[230:233], v[218:221], v[18:33]
	s_waitcnt lgkmcnt(8)
	v_mfma_f32_32x32x16_bf16 v[2:17], v[234:237], v[218:221], v[2:17]
	s_setprio 0
	ds_read_b64_tr_b16 v[210:211], v201 offset:61440
	ds_read_b64_tr_b16 v[212:213], v202 offset:63488
	ds_read_b64_tr_b16 v[218:219], v203 offset:61440
	ds_read_b64_tr_b16 v[220:221], v204 offset:63488
	ds_read_b64_tr_b16 v[202:203], v205 offset:61440
	ds_read_b64_tr_b16 v[204:205], v206 offset:63488
	ds_read_b64_tr_b16 v[206:207], v207 offset:61440
	ds_read_b64_tr_b16 v[208:209], v208 offset:63488
	s_setprio 1
	s_waitcnt lgkmcnt(14)
	v_mfma_f32_32x32x16_bf16 v[50:65], v[146:149], v[214:217], v[50:65]
	s_waitcnt lgkmcnt(12)
	v_mfma_f32_32x32x16_bf16 v[34:49], v[150:153], v[214:217], v[34:49]
	s_waitcnt lgkmcnt(10)
	v_mfma_f32_32x32x16_bf16 v[18:33], v[154:157], v[214:217], v[18:33]
	s_waitcnt lgkmcnt(8)
	v_mfma_f32_32x32x16_bf16 v[2:17], v[158:161], v[214:217], v[2:17]
	s_setprio 0
	s_setprio 1
	s_waitcnt lgkmcnt(6)
	v_mfma_f32_32x32x16_bf16 v[50:65], v[210:213], v[238:241], v[50:65]
	s_waitcnt lgkmcnt(4)
	v_mfma_f32_32x32x16_bf16 v[34:49], v[218:221], v[238:241], v[34:49]
	s_waitcnt lgkmcnt(2)
	v_mfma_f32_32x32x16_bf16 v[18:33], v[202:205], v[238:241], v[18:33]
	s_waitcnt lgkmcnt(0)
	v_mfma_f32_32x32x16_bf16 v[2:17], v[206:209], v[238:241], v[2:17]
	s_setprio 0
